# SWA attention: cross-half row max via v_permlane32_swap instead of ds_bpermute round trip
# speedup vs baseline: 1.0068x; 1.0068x over previous
; #define LAS __attribute__((address_space(3)))
; DI float xmax32(float v) { return fmaxf(v, __shfl_xor(v, 32)); }
;     DI const char* a(const Unit& u) const { return (const char*)(A + (size_t)u.pm * BM * lda); }
;     DI const char* a(const Unit& u) const { return (const char*)(A + (size_t)u.pm * BM * 2048 + (u.pn >> 1) * 512); }
;     DI const char* a(const Unit& u) const { return (const char*)((u.pn < 12 ? A1 : A2) + (size_t)u.pm * BM * 512); }
; template <int NDB, int VSTR>
; DI void softmax_pv(const f32x16& sacc, float& m, float& l, f32x16 (&oacc)[NDB], LAS const unsigned char* vptr) {
;     float mx = sacc[0];
; #pragma unroll
;     for (int i = 1; i < 16; ++i) mx = fmaxf(mx, sacc[i]);
;     mx = xmax32(mx);
;     if (__any(mx > m + 8.0f)) {
; DI void swa_attn_phase(const Params& p, LAS unsigned char* lds) {
;     ...
;             const int k0 = kstart + blk * 32;
;             if (k0 < 0 || k0 >= S) continue;
;             f32x16 sacc;
; #pragma unroll
;             for (int i = 0; i < 16; ++i) sacc[i] = 0.f;
; #pragma unroll
;             for (int ks = 0; ks < 4; ++ks) { const bf16x8 a = *(LAS const bf16x8*)(lds + (blk * 32 + r) * KSTR + ks * 32 + h * 16);
;                 sacc = __builtin_amdgcn_mfma_f32_32x32x16_bf16(a, qf[ks], sacc, 0, 0, 0); }
; #pragma unroll
;             for (int i = 0; i < 16; ++i) { const int key = k0 + (i & 3) + 8 * (i >> 2) + 4 * h;
;                 const int dk = qi - key, dp = pq - p.positions[key];
;                 const float sv = sacc[i] - slope2 * (float)(dp < 0 ? -dp : dp);
;                 sacc[i] = ((dk < 0 ? -dk : dk) <= 128) ? sv : -INFINITY; }
.LBB1_851:
	s_cmpk_gt_u32 s23, 0xfff
	s_cbranch_scc1 .LBB1_850
	v_add_u32_e32 v64, s23, v66
	v_lshl_add_u64 v[80:81], v[64:65], 2, s[10:11]
	ds_read_b128 v[32:35], v93
	ds_read_b128 v[98:101], v93 offset:32
	global_load_dwordx4 v[102:105], v[80:81], off
	global_load_dwordx4 v[108:111], v[80:81], off offset:32
	global_load_dwordx4 v[112:115], v[80:81], off offset:64
	global_load_dwordx4 v[116:119], v[80:81], off offset:96
	s_waitcnt lgkmcnt(0)
	v_mfma_f32_32x32x16_bf16 v[32:47], v[32:35], v[48:51], 0
	s_waitcnt vmcnt(0)
	v_sub_u32_e32 v64, v92, v102
	v_mfma_f32_32x32x16_bf16 v[32:47], v[98:101], v[52:55], v[32:47]
	ds_read_b128 v[98:101], v93 offset:64
	s_waitcnt lgkmcnt(0)
	v_mfma_f32_32x32x16_bf16 v[32:47], v[98:101], v[56:59], v[32:47]
	ds_read_b128 v[98:101], v93 offset:96
	s_waitcnt lgkmcnt(0)
	v_mfma_f32_32x32x16_bf16 v[32:47], v[98:101], v[60:63], v[32:47]
	v_sub_u32_e32 v99, 0, v64
	v_max_i32_e32 v64, v64, v99
	v_cvt_f32_u32_e32 v64, v64
	v_add_u32_e32 v101, s12, v88
	v_add_u32_e32 v98, 0x80, v101
	v_add_u32_e32 v102, 0x78, v101
	s_nop 5
	v_fma_f32 v32, -v96, v64, v32
	v_sub_u32_e32 v64, 0xffffff80, v101
	v_max_i32_e32 v64, v98, v64
	v_sub_u32_e32 v98, v92, v103
	v_sub_u32_e32 v99, 0, v98
	v_max_i32_e32 v98, v98, v99
	v_cvt_f32_u32_e32 v98, v98
	v_cmp_gt_u32_e32 vcc, s22, v64
	v_fma_f32 v33, -v96, v98, v33
	s_nop 0
	v_cndmask_b32_e32 v64, v91, v32, vcc
	v_add_u32_e32 v32, 0x7f, v101
	v_sub_u32_e32 v98, 0xffffff81, v101
	v_max_i32_e32 v32, v32, v98
	v_cmp_gt_u32_e32 vcc, s22, v32
	v_add_u32_e32 v32, 0x7e, v101
	s_nop 0
	v_cndmask_b32_e32 v99, v91, v33, vcc
	v_sub_u32_e32 v33, v92, v104
	v_sub_u32_e32 v98, 0, v33
	v_max_i32_e32 v33, v33, v98
	v_cvt_f32_u32_e32 v33, v33
	v_fma_f32 v33, -v96, v33, v34
	v_sub_u32_e32 v34, 0xffffff82, v101
	v_max_i32_e32 v32, v32, v34
	v_cmp_gt_u32_e32 vcc, s22, v32
	v_add_u32_e32 v32, 0x7d, v101
	s_nop 0
	v_cndmask_b32_e32 v100, v91, v33, vcc
	v_sub_u32_e32 v33, v92, v105
	v_sub_u32_e32 v34, 0, v33
	v_max_i32_e32 v33, v33, v34
	v_cvt_f32_u32_e32 v33, v33
	v_sub_u32_e32 v34, 0xffffff83, v101
	v_max_i32_e32 v32, v32, v34
	v_cmp_gt_u32_e32 vcc, s22, v32
	v_fma_f32 v33, -v96, v33, v35
	s_nop 0
	v_cndmask_b32_e32 v98, v91, v33, vcc
	v_mov_b32_e32 v32, v108
	v_mov_b32_e32 v33, v109
	v_mov_b32_e32 v34, v110
	v_mov_b32_e32 v35, v111
	s_nop 0
	v_sub_u32_e32 v32, v92, v32
	v_sub_u32_e32 v103, 0, v32
	v_max_i32_e32 v32, v32, v103
	v_cvt_f32_u32_e32 v32, v32
	v_sub_u32_e32 v33, v92, v33
	v_fma_f32 v32, -v96, v32, v36
	v_sub_u32_e32 v36, 0xffffff88, v101
	v_max_i32_e32 v36, v102, v36
	v_cmp_gt_u32_e32 vcc, s22, v36
	v_sub_u32_e32 v36, 0, v33
	v_max_i32_e32 v33, v33, v36
	v_cvt_f32_u32_e32 v33, v33
	v_cndmask_b32_e32 v102, v91, v32, vcc
	v_add_u32_e32 v32, 0x77, v101
	v_sub_u32_e32 v36, 0xffffff89, v101
	v_max_i32_e32 v32, v32, v36
	v_fma_f32 v33, -v96, v33, v37
	v_cmp_gt_u32_e32 vcc, s22, v32
	v_add_u32_e32 v32, 0x76, v101
	s_nop 0
	v_cndmask_b32_e32 v103, v91, v33, vcc
	v_sub_u32_e32 v33, v92, v34
	v_sub_u32_e32 v34, 0, v33
	v_max_i32_e32 v33, v33, v34
	v_cvt_f32_u32_e32 v33, v33
	v_sub_u32_e32 v34, 0xffffff8a, v101
	v_max_i32_e32 v32, v32, v34
	v_cmp_gt_u32_e32 vcc, s22, v32
	v_fma_f32 v33, -v96, v33, v38
	v_add_u32_e32 v32, 0x75, v101
	v_cndmask_b32_e32 v36, v91, v33, vcc
	v_sub_u32_e32 v33, v92, v35
	v_sub_u32_e32 v34, 0, v33
	v_max_i32_e32 v33, v33, v34
	v_cvt_f32_u32_e32 v33, v33
	v_sub_u32_e32 v34, 0xffffff8b, v101
	v_max_i32_e32 v32, v32, v34
	v_cmp_gt_u32_e32 vcc, s22, v32
	v_fma_f32 v33, -v96, v33, v39
	v_add_u32_e32 v38, 0x70, v101
	v_cndmask_b32_e32 v37, v91, v33, vcc
	v_mov_b32_e32 v32, v112
	v_mov_b32_e32 v33, v113
	v_mov_b32_e32 v34, v114
	v_mov_b32_e32 v35, v115
	s_nop 0
	v_sub_u32_e32 v32, v92, v32
	v_sub_u32_e32 v39, 0, v32
	v_max_i32_e32 v32, v32, v39
	v_sub_u32_e32 v39, 0xffffff90, v101
	v_cvt_f32_u32_e32 v32, v32
	v_max_i32_e32 v38, v38, v39
	v_sub_u32_e32 v33, v92, v33
	v_cmp_gt_u32_e32 vcc, s22, v38
	v_sub_u32_e32 v38, 0, v33
	v_max_i32_e32 v33, v33, v38
	v_cvt_f32_u32_e32 v33, v33
	v_fma_f32 v32, -v96, v32, v40
	v_cndmask_b32_e32 v39, v91, v32, vcc
	v_add_u32_e32 v32, 0x6f, v101
	v_sub_u32_e32 v38, 0xffffff91, v101
	v_max_i32_e32 v32, v32, v38
	v_fma_f32 v33, -v96, v33, v41
	v_cmp_gt_u32_e32 vcc, s22, v32
	v_add_u32_e32 v32, 0x6e, v101
	s_nop 0
	v_cndmask_b32_e32 v40, v91, v33, vcc
	v_sub_u32_e32 v33, v92, v34
	v_sub_u32_e32 v34, 0, v33
	v_max_i32_e32 v33, v33, v34
	v_cvt_f32_u32_e32 v33, v33
	v_sub_u32_e32 v34, 0xffffff92, v101
	v_max_i32_e32 v32, v32, v34
	v_cmp_gt_u32_e32 vcc, s22, v32
	v_fma_f32 v33, -v96, v33, v42
	v_add_u32_e32 v32, 0x6d, v101
	v_cndmask_b32_e32 v38, v91, v33, vcc
	v_sub_u32_e32 v33, v92, v35
	v_sub_u32_e32 v34, 0, v33
	v_max_i32_e32 v33, v33, v34
	v_cvt_f32_u32_e32 v33, v33
	v_sub_u32_e32 v34, 0xffffff93, v101
	v_max_i32_e32 v32, v32, v34
	v_cmp_gt_u32_e32 vcc, s22, v32
	v_fma_f32 v33, -v96, v33, v43
	v_add_u32_e32 v42, 0x68, v101
	v_cndmask_b32_e32 v41, v91, v33, vcc
	v_mov_b32_e32 v32, v116
	v_mov_b32_e32 v33, v117
	v_mov_b32_e32 v34, v118
	v_mov_b32_e32 v35, v119
	s_nop 0
	v_sub_u32_e32 v32, v92, v32
	v_sub_u32_e32 v43, 0, v32
	v_max_i32_e32 v32, v32, v43
	v_sub_u32_e32 v43, 0xffffff98, v101
	v_sub_u32_e32 v33, v92, v33
	v_cvt_f32_u32_e32 v32, v32
	v_max_i32_e32 v42, v42, v43
	v_sub_u32_e32 v43, 0, v33
	v_cmp_gt_u32_e32 vcc, s22, v42
	v_add_u32_e32 v42, 0x67, v101
	v_max_i32_e32 v33, v33, v43
	v_sub_u32_e32 v43, 0xffffff99, v101
	v_sub_u32_e32 v34, v92, v34
	v_cvt_f32_u32_e32 v33, v33
	v_max_i32_e32 v42, v42, v43
	v_sub_u32_e32 v43, 0, v34
	v_max_i32_e32 v34, v34, v43
	v_fma_f32 v32, -v96, v32, v44
	v_cvt_f32_u32_e32 v34, v34
	v_cndmask_b32_e32 v32, v91, v32, vcc
	v_cmp_gt_u32_e32 vcc, s22, v42
	v_add_u32_e32 v42, 0x66, v101
	v_sub_u32_e32 v43, 0xffffff9a, v101
	v_sub_u32_e32 v35, v92, v35
	v_fma_f32 v33, -v96, v33, v45
	v_max_i32_e32 v42, v42, v43
	v_sub_u32_e32 v43, 0, v35
	v_cndmask_b32_e32 v33, v91, v33, vcc
	v_cmp_gt_u32_e32 vcc, s22, v42
	v_add_u32_e32 v42, 0x65, v101
	v_max_i32_e32 v35, v35, v43
	v_sub_u32_e32 v43, 0xffffff9b, v101
	v_fma_f32 v34, -v96, v34, v46
	v_max_i32_e32 v42, v42, v43
	v_cndmask_b32_e32 v34, v91, v34, vcc
	v_cmp_gt_u32_e32 vcc, s22, v42
	v_max_f32_e32 v42, v64, v99
	v_cvt_f32_u32_e32 v35, v35
	v_max3_f32 v42, v42, v100, v98
	v_max3_f32 v42, v42, v102, v103
	v_max3_f32 v42, v42, v36, v37
	v_max3_f32 v42, v42, v39, v40
	v_fma_f32 v35, -v96, v35, v47
	v_max3_f32 v42, v42, v38, v41
	v_cndmask_b32_e32 v35, v91, v35, vcc
	v_max3_f32 v42, v42, v32, v33
	v_max3_f32 v42, v42, v34, v35
	v_mov_b32_e32 v43, v42
	s_nop 1
	v_permlane32_swap_b32_e32 v43, v42
	v_max_f32_e32 v42, v42, v43
	v_add_f32_e32 v43, 0x41000000, v97
	v_cmp_gt_f32_e32 vcc, v42, v43
	s_cbranch_vccz .LBB1_849
; DI float fast_exp2(float x) { return __builtin_amdgcn_exp2f(x); }
; template <int NDB, int VSTR>
; DI void softmax_pv(const f32x16& sacc, float& m, float& l, f32x16 (&oacc)[NDB], LAS const unsigned char* vptr) {
;     ...
;     if (__any(mx > m + 8.0f)) {
;         const float mn = fmaxf(m, mx), alpha = fast_exp2(m - mn);
;         l *= alpha; m = mn;
; #pragma unroll
;         for (int db = 0; db < NDB; ++db)
; #pragma unroll
;             for (int i = 0; i < 16; ++i) oacc[db][i] *= alpha;
;     }
	v_max_f32_e32 v42, v42, v42
	v_max_f32_e32 v43, v97, v97
	v_max_f32_e32 v43, v43, v42
	v_sub_f32_e32 v42, v97, v43
	v_exp_f32_e32 v42, v42
	v_mov_b32_e32 v97, v43
	v_mul_f32_e32 v75, v75, v42
	v_pk_mul_f32 v[14:15], v[14:15], v[42:43] op_sel_hi:[1,0]
	v_pk_mul_f32 v[12:13], v[12:13], v[42:43] op_sel_hi:[1,0]
	v_pk_mul_f32 v[10:11], v[10:11], v[42:43] op_sel_hi:[1,0]
	v_pk_mul_f32 v[8:9], v[8:9], v[42:43] op_sel_hi:[1,0]
	v_pk_mul_f32 v[6:7], v[6:7], v[42:43] op_sel_hi:[1,0]
	v_pk_mul_f32 v[4:5], v[4:5], v[42:43] op_sel_hi:[1,0]
	v_pk_mul_f32 v[2:3], v[2:3], v[42:43] op_sel_hi:[1,0]
	v_pk_mul_f32 v[0:1], v[0:1], v[42:43] op_sel_hi:[1,0]
	v_pk_mul_f32 v[30:31], v[30:31], v[42:43] op_sel_hi:[1,0]
	v_pk_mul_f32 v[28:29], v[28:29], v[42:43] op_sel_hi:[1,0]
	v_pk_mul_f32 v[26:27], v[26:27], v[42:43] op_sel_hi:[1,0]
	v_pk_mul_f32 v[24:25], v[24:25], v[42:43] op_sel_hi:[1,0]
	v_pk_mul_f32 v[22:23], v[22:23], v[42:43] op_sel_hi:[1,0]
	v_pk_mul_f32 v[20:21], v[20:21], v[42:43] op_sel_hi:[1,0]
	v_pk_mul_f32 v[18:19], v[18:19], v[42:43] op_sel_hi:[1,0]
	v_pk_mul_f32 v[16:17], v[16:17], v[42:43] op_sel_hi:[1,0]
	s_branch .LBB1_849
